# odd-layer prep phase: workgroups that own a compression-GEMM tile skip the ks/kw head-norm loops, the other 128 take all rows; FoX pair path: first group of c2l LDS reads issued under the last five sc
# baseline (speedup 1.0000x reference)
; #define NEG_INF (-__builtin_inff())
; #define LAS __attribute__((address_space(3)))
; DI int crow(int i, int g) { return (i & 3) + 8 * (i >> 2) + 4 * g; }
; DI void fox_block(const Params& p, int e, int bh, int j) {
;     ...
;     if (kb <= tile) {
;       f32x16 acca = score_tile_lds(qf, sg, L); __builtin_amdgcn_sched_barrier(0); f32x16 accb = score_tile_lds(qf, sg + AT_STAGE, L); __builtin_amdgcn_sched_barrier(0);
;       float sa[16], sb[16];
; #pragma unroll
;       for (int q = 0; q < 4; ++q) {
;         const f32x4 ca = *(const LAS f32x4*)(c2l + ka * 32 + 8 * q + 4 * g), cb = *(const LAS f32x4*)(c2l + kb * 32 + 8 * q + 4 * g);
; #pragma unroll
;         for (int e2 = 0; e2 < 4; ++e2) { sa[q * 4 + e2] = acca[q * 4 + e2] - ca[e2]; sb[q * 4 + e2] = accb[q * 4 + e2] - cb[e2]; }
;       }
;       if (kb == tile) {
; #pragma unroll
;         for (int q = 0; q < 16; ++q) sb[q] = (crow(q, g) <= lr) ? sb[q] : NEG_INF;
;       }
.LBB0_329:
	s_andn2_b64 vcc, exec, s[8:9]
	s_cbranch_vccnz .LBB0_335
	v_add_u32_e32 v0, s16, v211
	v_add_u32_e32 v6, v0, v213
	v_add_u32_e32 v7, v0, v214
	v_add_u32_e32 v8, v0, v215
	v_add_u32_e32 v9, v0, v216
	v_add_u32_e32 v10, v0, v217
	v_add_u32_e32 v11, v0, v218
	v_add_u32_e32 v12, v0, v219
	v_add_u32_e32 v0, v0, v220
	ds_read_b128 v[228:231], v6
	ds_read_b128 v[232:235], v7
	ds_read_b128 v[236:239], v8
	ds_read_b128 v[240:243], v9
	ds_read_b128 v[244:247], v10
	s_waitcnt lgkmcnt(4)
	v_mfma_f32_32x32x16_bf16 v[80:95], v[228:231], v[172:175], 0
	ds_read_b128 v[228:231], v11
	s_waitcnt lgkmcnt(4)
	v_mfma_f32_32x32x16_bf16 v[80:95], v[232:235], v[168:171], v[80:95]
	ds_read_b128 v[232:235], v12
	s_waitcnt lgkmcnt(4)
	v_mfma_f32_32x32x16_bf16 v[80:95], v[236:239], v[164:167], v[80:95]
	ds_read_b128 v[236:239], v0
	s_waitcnt lgkmcnt(4)
	v_mfma_f32_32x32x16_bf16 v[80:95], v[240:243], v[160:163], v[80:95]
	ds_read_b128 v[240:243], v6 offset:16384
	s_waitcnt lgkmcnt(4)
	v_mfma_f32_32x32x16_bf16 v[80:95], v[244:247], v[156:159], v[80:95]
	ds_read_b128 v[244:247], v7 offset:16384
	s_waitcnt lgkmcnt(4)
	v_mfma_f32_32x32x16_bf16 v[80:95], v[228:231], v[152:155], v[80:95]
	ds_read_b128 v[228:231], v8 offset:16384
	s_waitcnt lgkmcnt(4)
	v_mfma_f32_32x32x16_bf16 v[80:95], v[232:235], v[148:151], v[80:95]
	ds_read_b128 v[232:235], v9 offset:16384
	s_waitcnt lgkmcnt(4)
	v_mfma_f32_32x32x16_bf16 v[80:95], v[236:239], v[144:147], v[80:95]
	ds_read_b128 v[236:239], v10 offset:16384
	s_waitcnt lgkmcnt(4)
	v_mfma_f32_32x32x16_bf16 v[96:111], v[240:243], v[172:175], 0
	ds_read_b128 v[240:243], v11 offset:16384
	s_waitcnt lgkmcnt(4)
	v_mfma_f32_32x32x16_bf16 v[96:111], v[244:247], v[168:171], v[96:111]
	ds_read_b128 v[244:247], v12 offset:16384
	s_waitcnt lgkmcnt(4)
	v_mfma_f32_32x32x16_bf16 v[96:111], v[228:231], v[164:167], v[96:111]
	ds_read_b128 v[228:231], v0 offset:16384
	v_add_u32_e32 v0, s14, v221
	v_add_u32_e32 v2, 0x10000, v0
	v_add_u32_e32 v6, 0x10080, v0
	ds_read_b128 v[2:5], v2
	ds_read_b128 v[6:9], v6
	v_add_u32_e32 v10, 0x100a0, v0
	ds_read_b128 v[10:13], v10
	s_waitcnt lgkmcnt(7)
	v_mfma_f32_32x32x16_bf16 v[96:111], v[232:235], v[160:163], v[96:111]
	s_waitcnt lgkmcnt(6)
	v_mfma_f32_32x32x16_bf16 v[96:111], v[236:239], v[156:159], v[96:111]
	s_waitcnt lgkmcnt(5)
	v_mfma_f32_32x32x16_bf16 v[96:111], v[240:243], v[152:155], v[96:111]
	s_waitcnt lgkmcnt(4)
	v_mfma_f32_32x32x16_bf16 v[96:111], v[244:247], v[148:151], v[96:111]
	s_waitcnt lgkmcnt(3)
	v_mfma_f32_32x32x16_bf16 v[96:111], v[228:231], v[144:147], v[96:111]
	s_cmp_lg_u32 s12, s15
	s_waitcnt lgkmcnt(0)
	s_nop 6
	s_nop 2
	v_pk_add_f32 v[112:113], v[96:97], v[6:7] neg_lo:[0,1] neg_hi:[0,1]
	v_add_u32_e32 v96, 0x100c0, v0
	v_pk_add_f32 v[14:15], v[98:99], v[8:9] neg_lo:[0,1] neg_hi:[0,1]
	ds_read_b128 v[96:99], v96
	v_add_u32_e32 v6, 0x10020, v0
	v_pk_add_f32 v[114:115], v[100:101], v[10:11] neg_lo:[0,1] neg_hi:[0,1]
	v_add_u32_e32 v10, 0x10040, v0
	ds_read_b128 v[6:9], v6
	s_waitcnt lgkmcnt(0)
	v_pk_add_f32 v[104:105], v[104:105], v[96:97] neg_lo:[0,1] neg_hi:[0,1]
	v_add_u32_e32 v96, 0x10060, v0
	v_add_u32_e32 v0, 0x100e0, v0
	ds_read_b128 v[116:119], v0
	v_pk_add_f32 v[102:103], v[102:103], v[12:13] neg_lo:[0,1] neg_hi:[0,1]
	ds_read_b128 v[10:13], v10
	v_pk_add_f32 v[100:101], v[106:107], v[98:99] neg_lo:[0,1] neg_hi:[0,1]
	ds_read_b128 v[96:99], v96
	s_waitcnt lgkmcnt(0)
	v_pk_add_f32 v[108:109], v[108:109], v[116:117] neg_lo:[0,1] neg_hi:[0,1]
	v_pk_add_f32 v[106:107], v[110:111], v[118:119] neg_lo:[0,1] neg_hi:[0,1]
	s_cbranch_scc1 .LBB0_332
	v_cndmask_b32_e64 v112, v112, v248, s[38:39]
	v_cndmask_b32_e64 v113, v248, v113, s[40:41]
	v_cndmask_b32_e64 v14, v14, v248, s[42:43]
	v_cndmask_b32_e64 v15, v15, v248, s[44:45]
	v_cndmask_b32_e64 v114, v114, v248, s[46:47]
	v_cndmask_b32_e64 v115, v115, v248, s[48:49]
	v_cndmask_b32_e64 v102, v102, v248, s[50:51]
	v_cndmask_b32_e64 v103, v103, v248, s[52:53]
	v_cndmask_b32_e64 v104, v104, v248, s[54:55]
	v_cndmask_b32_e64 v105, v105, v248, s[56:57]
	v_cndmask_b32_e64 v100, v100, v248, s[58:59]
	v_cndmask_b32_e64 v101, v101, v248, s[60:61]
	v_cndmask_b32_e64 v108, v108, v248, s[62:63]
	v_cndmask_b32_e64 v109, v109, v248, s[64:65]
	v_cndmask_b32_e64 v106, v106, v248, s[66:67]
	v_cndmask_b32_e64 v107, v107, v248, s[68:69]

; #define TIDX launder((int)threadIdx.x)
; DI float bf2f(bf16_t v) { return __uint_as_float(((unsigned)v) << 16); }
; DI void headnorm_rows(bf16_t* buf, int rows, const float* __restrict__ gain, int item0, int nitems_total) {
;   const int lane = TIDX & 63, gw = blockIdx.x * 8 + (TIDX >> 6), nw = gridDim.x * 8;
;   const int sub = lane >> 4, l16 = lane & 15;
;   (void)item0; (void)nitems_total;
;   for (int it = gw; it < rows / 4; it += nw) {
;     bf16_t* rp = buf + (size_t)(it * 4 + sub) * 128 + l16 * 8;
;     bf16x8 raw = *(const bf16x8*)rp;
;     float f[8], s = 0.f;
; #pragma unroll
;     for (int e = 0; e < 8; ++e) { f[e] = bf2f((bf16_t)raw[e]); s += f[e] * f[e]; }
; DI void run_phase(const Params& p0, int ph) {
;     ...
;         headnorm_rows((bf16_t*)(ws + O_KS), 8 * T_, p.in[16] + (e * 3 + 1) * 128, 0, 0);
.LBB0_342:
	s_andn2_b64 vcc, exec, s[0:1]
	s_mov_b64 s[2:3], 0
	s_cbranch_vccnz .LBB0_374
	v_readlane_b32 s0, v254, 24
	s_cmp_gt_i32 s0, 1
	s_mov_b64 s[0:1], -1
	s_cbranch_scc0 .LBB0_372
	v_readlane_b32 s2, v254, 16
	v_readlane_b32 s3, v254, 17
	s_and_b64 vcc, exec, s[2:3]
	s_cbranch_vccz .LBB0_361
	v_readlane_b32 s0, v254, 20
	v_readlane_b32 s1, v254, 21
	v_mov_b32_e32 v2, v199
	v_mov_b32_e32 v0, v199
	v_readlane_b32 s1, v250, 11
	v_ashrrev_i32_e32 v6, 6, v0
	s_mulk_i32 s0, 0x180
	s_sub_i32 s1, s1, 0x400
	v_add_u32_e32 v0, s1, v6
	v_cmp_gt_u32_e32 vcc, s81, v0
	s_and_saveexec_b64 s[2:3], vcc
	v_readlane_b32 s8, v252, 43
	v_readlane_b32 s9, v252, 44
	s_mov_b32 s9, 0x800000
	s_movk_i32 s10, 0x1fff
	s_lshr_b32 s8, s8, 1
	s_cbranch_execz .LBB0_348
	v_bfe_u32 v7, v2, 4, 2
	s_ashr_i32 s1, s0, 31
	v_lshlrev_b32_e32 v2, 3, v2
	s_lshl_b64 s[4:5], s[0:1], 2
	v_readlane_b32 s12, v253, 30
	v_and_b32_e32 v4, 0x78, v2
	v_readlane_b32 s6, v253, 48
	v_readlane_b32 s13, v253, 31
	s_add_u32 s4, s12, s4
	v_lshlrev_b32_e32 v2, 1, v4
	s_waitcnt lgkmcnt(0)
	v_mov_b32_e32 v3, v1
	v_readlane_b32 s7, v253, 49
	s_addc_u32 s5, s13, s5
	v_lshlrev_b32_e32 v4, 2, v4
	v_lshl_add_u64 v[2:3], s[6:7], 0, v[2:3]
	s_mov_b64 s[6:7], 0x28165000
	v_mov_b32_e32 v5, v1
	v_lshlrev_b32_e32 v6, 2, v6
	v_readlane_b32 s1, v252, 35
	v_lshl_add_u64 v[2:3], v[2:3], 0, s[6:7]
	v_lshl_add_u64 v[4:5], s[4:5], 0, v[4:5]
	s_sub_i32 s1, s1, 0x1000
	v_add3_u32 v6, s1, v6, v7
	v_readlane_b32 s1, v252, 36
	s_mov_b64 s[4:5], 0
	v_readlane_b32 s14, v253, 32
	v_readlane_b32 s15, v253, 33
	v_readlane_b32 s16, v253, 34
	v_readlane_b32 s17, v253, 35
	v_readlane_b32 s18, v253, 36
	v_readlane_b32 s19, v253, 37
	v_readlane_b32 s20, v253, 38
	v_readlane_b32 s21, v253, 39
	v_readlane_b32 s22, v253, 40
	v_readlane_b32 s23, v253, 41
	v_readlane_b32 s24, v253, 42
	v_readlane_b32 s25, v253, 43
	v_readlane_b32 s26, v253, 44
	v_readlane_b32 s27, v253, 45
	s_lshr_b32 s1, s1, 1
	global_load_dwordx4 v[44:47], v[4:5], off offset:528
	global_load_dwordx4 v[48:51], v[4:5], off offset:512
	v_ashrrev_i32_e32 v7, 31, v6
	v_lshlrev_b64 v[8:9], 8, v[6:7]
	v_lshl_add_u64 v[18:19], v[2:3], 0, v[8:9]
	global_load_dwordx4 v[8:11], v[18:19], off
	s_waitcnt vmcnt(0)

; #define TIDX launder((int)threadIdx.x)
; DI float bf2f(bf16_t v) { return __uint_as_float(((unsigned)v) << 16); }
; DI void headnorm_rows(bf16_t* buf, int rows, const float* __restrict__ gain, int item0, int nitems_total) {
;   const int lane = TIDX & 63, gw = blockIdx.x * 8 + (TIDX >> 6), nw = gridDim.x * 8;
;   const int sub = lane >> 4, l16 = lane & 15;
;   (void)item0; (void)nitems_total;
;   for (int it = gw; it < rows / 4; it += nw) {
;     bf16_t* rp = buf + (size_t)(it * 4 + sub) * 128 + l16 * 8;
;     bf16x8 raw = *(const bf16x8*)rp;
;     float f[8], s = 0.f;
; #pragma unroll
;     for (int e = 0; e < 8; ++e) { f[e] = bf2f((bf16_t)raw[e]); s += f[e] * f[e]; }
; DI void run_phase(const Params& p0, int ph) {
;     ...
;         headnorm_rows((bf16_t*)(ws + O_KW), 8 * T_, p.in[16] + (e * 3 + 2) * 128, 0, 0);
.LBB0_348:
	s_or_b64 exec, exec, s[2:3]
	v_mov_b32_e32 v2, v199
	v_mov_b32_e32 v0, v199
	v_readlane_b32 s1, v250, 11
	v_ashrrev_i32_e32 v6, 6, v0
	s_nop 0
	s_sub_i32 s1, s1, 0x400
	v_add_u32_e32 v0, s1, v6
	v_cmp_gt_u32_e32 vcc, s81, v0
	s_and_saveexec_b64 s[2:3], vcc
	v_readlane_b32 s6, v252, 43
	v_readlane_b32 s7, v252, 44
	v_readlane_b32 s7, v252, 36
	s_mov_b32 s8, 0x800000
	s_lshr_b32 s6, s6, 1
	s_lshr_b32 s7, s7, 1
	s_cbranch_execz .LBB0_351
	s_ashr_i32 s1, s0, 31
	v_bfe_u32 v7, v2, 4, 2
	s_lshl_b64 s[0:1], s[0:1], 2
	v_readlane_b32 s12, v253, 30
	v_lshlrev_b32_e32 v2, 3, v2
	v_readlane_b32 s13, v253, 31
	s_add_u32 s0, s12, s0
	v_and_b32_e32 v4, 0x78, v2
	v_readlane_b32 s4, v253, 48
	s_addc_u32 s1, s13, s1
	v_lshlrev_b32_e32 v2, 1, v4
	s_waitcnt lgkmcnt(0)
	v_mov_b32_e32 v3, v1
	v_readlane_b32 s5, v253, 49
	v_lshlrev_b32_e32 v4, 2, v4
	v_mov_b32_e32 v5, v1
	v_lshl_add_u64 v[2:3], s[4:5], 0, v[2:3]
	s_mov_b64 s[4:5], 0x28965000
	v_lshl_add_u64 v[4:5], s[0:1], 0, v[4:5]
	v_lshlrev_b32_e32 v6, 2, v6
	v_readlane_b32 s0, v252, 35
	v_lshl_add_u64 v[2:3], v[2:3], 0, s[4:5]
	v_readlane_b32 s14, v253, 32
	s_sub_i32 s0, s0, 0x1000
	v_add3_u32 v6, s0, v6, v7
	s_mov_b64 s[0:1], 0
	v_readlane_b32 s15, v253, 33
	v_readlane_b32 s16, v253, 34
	v_readlane_b32 s17, v253, 35
	v_readlane_b32 s18, v253, 36
	v_readlane_b32 s19, v253, 37
	v_readlane_b32 s20, v253, 38
	v_readlane_b32 s21, v253, 39
	v_readlane_b32 s22, v253, 40
	v_readlane_b32 s23, v253, 41
	v_readlane_b32 s24, v253, 42
	v_readlane_b32 s25, v253, 43
	v_readlane_b32 s26, v253, 44
	v_readlane_b32 s27, v253, 45
	global_load_dwordx4 v[44:47], v[4:5], off offset:1040
	global_load_dwordx4 v[48:51], v[4:5], off offset:1024
	v_ashrrev_i32_e32 v7, 31, v6
	v_lshlrev_b64 v[8:9], 8, v[6:7]
	v_lshl_add_u64 v[18:19], v[2:3], 0, v[8:9]
	global_load_dwordx4 v[8:11], v[18:19], off
	s_waitcnt vmcnt(0)
